# split-K partial tile stored/loaded with sc0 sc1 scope bits (write-through, coherent read) so the per-WG buffer_wbl2 and buffer_inv on that handoff are gone
# speedup vs baseline: 1.0168x; 1.0057x over previous
.Lm2_spin_ok:
.Lm2_spin_done:
	s_barrier
	global_load_dwordx4 v[210:213], v186, s[100:101] sc0 sc1
	s_add_u32 s100, s100, 0x2000
	s_addc_u32 s101, s101, 0
	global_load_dwordx4 v[214:217], v186, s[100:101] sc0 sc1
	s_add_u32 s100, s100, 0x2000
	s_addc_u32 s101, s101, 0
	global_load_dwordx4 v[218:221], v186, s[100:101] sc0 sc1
	s_add_u32 s100, s100, 0x2000
	s_addc_u32 s101, s101, 0
	global_load_dwordx4 v[222:225], v186, s[100:101] sc0 sc1
	s_add_u32 s100, s100, 0x2000
	s_addc_u32 s101, s101, 0
	global_load_dwordx4 v[226:229], v186, s[100:101] sc0 sc1
	s_add_u32 s100, s100, 0x2000
	s_addc_u32 s101, s101, 0
	global_load_dwordx4 v[230:233], v186, s[100:101] sc0 sc1
	s_add_u32 s100, s100, 0x2000
	s_addc_u32 s101, s101, 0
	global_load_dwordx4 v[234:237], v186, s[100:101] sc0 sc1
	s_add_u32 s100, s100, 0x2000
	s_addc_u32 s101, s101, 0
	global_load_dwordx4 v[238:241], v186, s[100:101] sc0 sc1
	s_add_u32 s100, s100, 0x2000
	s_addc_u32 s101, s101, 0
	s_waitcnt vmcnt(7)
	v_pk_add_f32 v[140:141], v[140:141], v[210:211]
	v_pk_add_f32 v[142:143], v[142:143], v[212:213]
	s_waitcnt vmcnt(6)
	v_pk_add_f32 v[128:129], v[128:129], v[214:215]
	v_pk_add_f32 v[130:131], v[130:131], v[216:217]
	s_waitcnt vmcnt(5)
	v_pk_add_f32 v[116:117], v[116:117], v[218:219]
	v_pk_add_f32 v[118:119], v[118:119], v[220:221]
	s_waitcnt vmcnt(4)
	v_pk_add_f32 v[108:109], v[108:109], v[222:223]
	v_pk_add_f32 v[110:111], v[110:111], v[224:225]
	s_waitcnt vmcnt(3)
	v_pk_add_f32 v[112:113], v[112:113], v[226:227]
	v_pk_add_f32 v[114:115], v[114:115], v[228:229]
	s_waitcnt vmcnt(2)
	v_pk_add_f32 v[104:105], v[104:105], v[230:231]
	v_pk_add_f32 v[106:107], v[106:107], v[232:233]
	s_waitcnt vmcnt(1)
	v_pk_add_f32 v[100:101], v[100:101], v[234:235]
	v_pk_add_f32 v[102:103], v[102:103], v[236:237]
	s_waitcnt vmcnt(0)
	v_pk_add_f32 v[92:93], v[92:93], v[238:239]
	v_pk_add_f32 v[94:95], v[94:95], v[240:241]
	global_load_dwordx4 v[210:213], v186, s[100:101] sc0 sc1
	s_add_u32 s100, s100, 0x2000
	s_addc_u32 s101, s101, 0
	global_load_dwordx4 v[214:217], v186, s[100:101] sc0 sc1
	s_add_u32 s100, s100, 0x2000
	s_addc_u32 s101, s101, 0
	global_load_dwordx4 v[218:221], v186, s[100:101] sc0 sc1
	s_add_u32 s100, s100, 0x2000
	s_addc_u32 s101, s101, 0
	global_load_dwordx4 v[222:225], v186, s[100:101] sc0 sc1
	s_add_u32 s100, s100, 0x2000
	s_addc_u32 s101, s101, 0
	global_load_dwordx4 v[226:229], v186, s[100:101] sc0 sc1
	s_add_u32 s100, s100, 0x2000
	s_addc_u32 s101, s101, 0
	global_load_dwordx4 v[230:233], v186, s[100:101] sc0 sc1
	s_add_u32 s100, s100, 0x2000
	s_addc_u32 s101, s101, 0
	global_load_dwordx4 v[234:237], v186, s[100:101] sc0 sc1
	s_add_u32 s100, s100, 0x2000
	s_addc_u32 s101, s101, 0
	global_load_dwordx4 v[238:241], v186, s[100:101] sc0 sc1
	s_add_u32 s100, s100, 0x2000
	s_addc_u32 s101, s101, 0
	s_waitcnt vmcnt(7)
	v_pk_add_f32 v[96:97], v[96:97], v[210:211]
	v_pk_add_f32 v[98:99], v[98:99], v[212:213]
	s_waitcnt vmcnt(6)
	v_pk_add_f32 v[88:89], v[88:89], v[214:215]
	v_pk_add_f32 v[90:91], v[90:91], v[216:217]
	s_waitcnt vmcnt(5)
	v_pk_add_f32 v[84:85], v[84:85], v[218:219]
	v_pk_add_f32 v[86:87], v[86:87], v[220:221]
	s_waitcnt vmcnt(4)
	v_pk_add_f32 v[76:77], v[76:77], v[222:223]
	v_pk_add_f32 v[78:79], v[78:79], v[224:225]
	s_waitcnt vmcnt(3)
	v_pk_add_f32 v[80:81], v[80:81], v[226:227]
	v_pk_add_f32 v[82:83], v[82:83], v[228:229]
	s_waitcnt vmcnt(2)
	v_pk_add_f32 v[72:73], v[72:73], v[230:231]
	v_pk_add_f32 v[74:75], v[74:75], v[232:233]
	s_waitcnt vmcnt(1)
	v_pk_add_f32 v[68:69], v[68:69], v[234:235]
	v_pk_add_f32 v[70:71], v[70:71], v[236:237]
	s_waitcnt vmcnt(0)
	v_pk_add_f32 v[64:65], v[64:65], v[238:239]
	v_pk_add_f32 v[66:67], v[66:67], v[240:241]
	global_load_dwordx4 v[210:213], v186, s[100:101] sc0 sc1
	s_add_u32 s100, s100, 0x2000
	s_addc_u32 s101, s101, 0
	global_load_dwordx4 v[214:217], v186, s[100:101] sc0 sc1
	s_add_u32 s100, s100, 0x2000
	s_addc_u32 s101, s101, 0
	global_load_dwordx4 v[218:221], v186, s[100:101] sc0 sc1
	s_add_u32 s100, s100, 0x2000
	s_addc_u32 s101, s101, 0
	global_load_dwordx4 v[222:225], v186, s[100:101] sc0 sc1
	s_add_u32 s100, s100, 0x2000
	s_addc_u32 s101, s101, 0
	global_load_dwordx4 v[226:229], v186, s[100:101] sc0 sc1
	s_add_u32 s100, s100, 0x2000
	s_addc_u32 s101, s101, 0
	global_load_dwordx4 v[230:233], v186, s[100:101] sc0 sc1
	s_add_u32 s100, s100, 0x2000
	s_addc_u32 s101, s101, 0
	global_load_dwordx4 v[234:237], v186, s[100:101] sc0 sc1
	s_add_u32 s100, s100, 0x2000
	s_addc_u32 s101, s101, 0
	global_load_dwordx4 v[238:241], v186, s[100:101] sc0 sc1
	s_add_u32 s100, s100, 0x2000
	s_addc_u32 s101, s101, 0
	s_waitcnt vmcnt(7)
	v_pk_add_f32 v[60:61], v[60:61], v[210:211]
	v_pk_add_f32 v[62:63], v[62:63], v[212:213]
	s_waitcnt vmcnt(6)
	v_pk_add_f32 v[56:57], v[56:57], v[214:215]
	v_pk_add_f32 v[58:59], v[58:59], v[216:217]
	s_waitcnt vmcnt(5)
	v_pk_add_f32 v[52:53], v[52:53], v[218:219]
	v_pk_add_f32 v[54:55], v[54:55], v[220:221]
	s_waitcnt vmcnt(4)
	v_pk_add_f32 v[44:45], v[44:45], v[222:223]
	v_pk_add_f32 v[46:47], v[46:47], v[224:225]
	s_waitcnt vmcnt(3)
	v_pk_add_f32 v[48:49], v[48:49], v[226:227]
	v_pk_add_f32 v[50:51], v[50:51], v[228:229]
	s_waitcnt vmcnt(2)
	v_pk_add_f32 v[40:41], v[40:41], v[230:231]
	v_pk_add_f32 v[42:43], v[42:43], v[232:233]
	s_waitcnt vmcnt(1)
	v_pk_add_f32 v[36:37], v[36:37], v[234:235]
	v_pk_add_f32 v[38:39], v[38:39], v[236:237]
	s_waitcnt vmcnt(0)
	v_pk_add_f32 v[28:29], v[28:29], v[238:239]
	v_pk_add_f32 v[30:31], v[30:31], v[240:241]
	global_load_dwordx4 v[210:213], v186, s[100:101] sc0 sc1
	s_add_u32 s100, s100, 0x2000
	s_addc_u32 s101, s101, 0
	global_load_dwordx4 v[214:217], v186, s[100:101] sc0 sc1
	s_add_u32 s100, s100, 0x2000
	s_addc_u32 s101, s101, 0
	global_load_dwordx4 v[218:221], v186, s[100:101] sc0 sc1
	s_add_u32 s100, s100, 0x2000
	s_addc_u32 s101, s101, 0
	global_load_dwordx4 v[222:225], v186, s[100:101] sc0 sc1
	s_add_u32 s100, s100, 0x2000
	s_addc_u32 s101, s101, 0
	global_load_dwordx4 v[226:229], v186, s[100:101] sc0 sc1
	s_add_u32 s100, s100, 0x2000
	s_addc_u32 s101, s101, 0
	global_load_dwordx4 v[230:233], v186, s[100:101] sc0 sc1
	s_add_u32 s100, s100, 0x2000
	s_addc_u32 s101, s101, 0
	global_load_dwordx4 v[234:237], v186, s[100:101] sc0 sc1
	s_add_u32 s100, s100, 0x2000
	s_addc_u32 s101, s101, 0
	global_load_dwordx4 v[238:241], v186, s[100:101] sc0 sc1
	s_add_u32 s100, s100, 0x2000
	s_addc_u32 s101, s101, 0
	s_waitcnt vmcnt(7)
	v_pk_add_f32 v[32:33], v[32:33], v[210:211]
	v_pk_add_f32 v[34:35], v[34:35], v[212:213]
	s_waitcnt vmcnt(6)
	v_pk_add_f32 v[24:25], v[24:25], v[214:215]
	v_pk_add_f32 v[26:27], v[26:27], v[216:217]
	s_waitcnt vmcnt(5)
	v_pk_add_f32 v[20:21], v[20:21], v[218:219]
	v_pk_add_f32 v[22:23], v[22:23], v[220:221]
	s_waitcnt vmcnt(4)
	v_pk_add_f32 v[12:13], v[12:13], v[222:223]
	v_pk_add_f32 v[14:15], v[14:15], v[224:225]
	s_waitcnt vmcnt(3)
	v_pk_add_f32 v[16:17], v[16:17], v[226:227]
	v_pk_add_f32 v[18:19], v[18:19], v[228:229]
	s_waitcnt vmcnt(2)
	v_pk_add_f32 v[8:9], v[8:9], v[230:231]
	v_pk_add_f32 v[10:11], v[10:11], v[232:233]
	s_waitcnt vmcnt(1)
	v_pk_add_f32 v[4:5], v[4:5], v[234:235]
	v_pk_add_f32 v[6:7], v[6:7], v[236:237]
	s_waitcnt vmcnt(0)
	v_pk_add_f32 v[0:1], v[0:1], v[238:239]
	v_pk_add_f32 v[2:3], v[2:3], v[240:241]
	s_branch .Lm2_epi
.Lm2_put_partial:
	s_nop 7
	s_nop 7
	global_store_dwordx4 v186, v[140:143], s[100:101] sc0 sc1
	s_add_u32 s100, s100, 0x2000
	s_addc_u32 s101, s101, 0
	global_store_dwordx4 v186, v[128:131], s[100:101] sc0 sc1
	s_add_u32 s100, s100, 0x2000
	s_addc_u32 s101, s101, 0
	global_store_dwordx4 v186, v[116:119], s[100:101] sc0 sc1
	s_add_u32 s100, s100, 0x2000
	s_addc_u32 s101, s101, 0
	global_store_dwordx4 v186, v[108:111], s[100:101] sc0 sc1
	s_add_u32 s100, s100, 0x2000
	s_addc_u32 s101, s101, 0
	global_store_dwordx4 v186, v[112:115], s[100:101] sc0 sc1
	s_add_u32 s100, s100, 0x2000
	s_addc_u32 s101, s101, 0
	global_store_dwordx4 v186, v[104:107], s[100:101] sc0 sc1
	s_add_u32 s100, s100, 0x2000
	s_addc_u32 s101, s101, 0
	global_store_dwordx4 v186, v[100:103], s[100:101] sc0 sc1
	s_add_u32 s100, s100, 0x2000
	s_addc_u32 s101, s101, 0
	global_store_dwordx4 v186, v[92:95], s[100:101] sc0 sc1
	s_add_u32 s100, s100, 0x2000
	s_addc_u32 s101, s101, 0
	global_store_dwordx4 v186, v[96:99], s[100:101] sc0 sc1
	s_add_u32 s100, s100, 0x2000
	s_addc_u32 s101, s101, 0
	global_store_dwordx4 v186, v[88:91], s[100:101] sc0 sc1
	s_add_u32 s100, s100, 0x2000
	s_addc_u32 s101, s101, 0
	global_store_dwordx4 v186, v[84:87], s[100:101] sc0 sc1
	s_add_u32 s100, s100, 0x2000
	s_addc_u32 s101, s101, 0
	global_store_dwordx4 v186, v[76:79], s[100:101] sc0 sc1
	s_add_u32 s100, s100, 0x2000
	s_addc_u32 s101, s101, 0
	global_store_dwordx4 v186, v[80:83], s[100:101] sc0 sc1
	s_add_u32 s100, s100, 0x2000
	s_addc_u32 s101, s101, 0
	global_store_dwordx4 v186, v[72:75], s[100:101] sc0 sc1
	s_add_u32 s100, s100, 0x2000
	s_addc_u32 s101, s101, 0
	global_store_dwordx4 v186, v[68:71], s[100:101] sc0 sc1
	s_add_u32 s100, s100, 0x2000
	s_addc_u32 s101, s101, 0
	global_store_dwordx4 v186, v[64:67], s[100:101] sc0 sc1
	s_add_u32 s100, s100, 0x2000
	s_addc_u32 s101, s101, 0
	global_store_dwordx4 v186, v[60:63], s[100:101] sc0 sc1
	s_add_u32 s100, s100, 0x2000
	s_addc_u32 s101, s101, 0
	global_store_dwordx4 v186, v[56:59], s[100:101] sc0 sc1
	s_add_u32 s100, s100, 0x2000
	s_addc_u32 s101, s101, 0
	global_store_dwordx4 v186, v[52:55], s[100:101] sc0 sc1
	s_add_u32 s100, s100, 0x2000
	s_addc_u32 s101, s101, 0
	global_store_dwordx4 v186, v[44:47], s[100:101] sc0 sc1
	s_add_u32 s100, s100, 0x2000
	s_addc_u32 s101, s101, 0
	global_store_dwordx4 v186, v[48:51], s[100:101] sc0 sc1
	s_add_u32 s100, s100, 0x2000
	s_addc_u32 s101, s101, 0
	global_store_dwordx4 v186, v[40:43], s[100:101] sc0 sc1
	s_add_u32 s100, s100, 0x2000
	s_addc_u32 s101, s101, 0
	global_store_dwordx4 v186, v[36:39], s[100:101] sc0 sc1
	s_add_u32 s100, s100, 0x2000
	s_addc_u32 s101, s101, 0
	global_store_dwordx4 v186, v[28:31], s[100:101] sc0 sc1
	s_add_u32 s100, s100, 0x2000
	s_addc_u32 s101, s101, 0
	global_store_dwordx4 v186, v[32:35], s[100:101] sc0 sc1
	s_add_u32 s100, s100, 0x2000
	s_addc_u32 s101, s101, 0
	global_store_dwordx4 v186, v[24:27], s[100:101] sc0 sc1
	s_add_u32 s100, s100, 0x2000
	s_addc_u32 s101, s101, 0
	global_store_dwordx4 v186, v[20:23], s[100:101] sc0 sc1
	s_add_u32 s100, s100, 0x2000
	s_addc_u32 s101, s101, 0
	global_store_dwordx4 v186, v[12:15], s[100:101] sc0 sc1
	s_add_u32 s100, s100, 0x2000
	s_addc_u32 s101, s101, 0
	global_store_dwordx4 v186, v[16:19], s[100:101] sc0 sc1
	s_add_u32 s100, s100, 0x2000
	s_addc_u32 s101, s101, 0
	global_store_dwordx4 v186, v[8:11], s[100:101] sc0 sc1
	s_add_u32 s100, s100, 0x2000
	s_addc_u32 s101, s101, 0
	global_store_dwordx4 v186, v[4:7], s[100:101] sc0 sc1
	s_add_u32 s100, s100, 0x2000
	s_addc_u32 s101, s101, 0
	global_store_dwordx4 v186, v[0:3], s[100:101] sc0 sc1
	s_add_u32 s100, s100, 0x2000
	s_addc_u32 s101, s101, 0
	s_waitcnt vmcnt(0)
	s_barrier
	s_cmpk_gt_u32 s42, 0x3f
	s_cbranch_scc1 .Lm2_epi_tail
	s_and_b32 s6, s2, 0x7f
	s_lshl_b32 s6, s6, 6
	s_add_u32 s6, s6, 0x2970a000
	s_add_u32 s6, s46, s6
	s_addc_u32 s7, s47, 0
	v_mov_b32_e32 v187, 0
	v_mov_b32_e32 v188, 8
	s_mov_b64 exec, 1
	global_atomic_add v187, v188, s[6:7]
	s_mov_b64 exec, -1
	s_branch .Lm2_epi_tail
